# hot loop headers (GEMM K-loops, attention main loop) aligned to 64 bytes with s_nop padding; plus global_* ops and deferred SSQ atomics
# speedup vs baseline: 1.0059x; 1.0059x over previous
;     __host__ __device__ bool next(int i, Unit& u) const { const long L = (long)i * G + c; if (L >= nun) return false; u.pz = (int)L / nM; u.pm = (int)L % nM; u.pn = 0; return true; }
;   __device__ __forceinline__ bool next(int i,AttnUnit&u)const{ const int v=vcu+(i>>2)*G; if(v>=256)return false; const int s=v&15,k=i&3; u.bh=v>>4; u.qb=(k&1)?(32*(k>>1)+31-s):(32*(k>>1)+s); return true; }
; template <class Epi, class Sched, bool ALIGN_EPI = false, bool SP2 = false>
; __device__ __forceinline__ void gemm_phase(PG8_LAS unsigned char* lds, const Gemm g, const Sched& S, const Epi& E, const int wid) {
;     ...
;         const bool has_next = S.next(ui + 1, nxt);
;         const char* nA = has_next ? PG8_APTR(nxt) : cA; const char* nB = has_next ? PG8_BPTR(nxt) : cB;
;         for (int t = 0; t < nt; t += 2) {
;             const bool last = (t == nt - 2);
;             const char* a1 = cA + (size_t)(t + 1) * kstep;
;             const char* a2 = last ? nA : cA + (size_t)(t + 2) * kstep; const char* b2 = last ? nB : cB + (size_t)(t + 2) * kstep;
;     ...
; #pragma unroll
;         for (int a = 0; a < 2; ++a)
; #pragma unroll
;             for (int b = 0; b < 2; ++b)
; #pragma unroll
;                 for (int m = 0; m < 4; ++m)
; #pragma unroll
;                     for (int n = 0; n < 2; ++n) acc[a][b][m][n] = (f32x4){0.f, 0.f, 0.f, 0.f};
;         cur = nxt; cA = nA; cB = nB; ++ui;
.LBB0_417:
	s_ashr_i32 s17, s16, 31
	s_lshl_b64 s[18:19], s[16:17], 20
	s_add_u32 s18, s3, s18
	s_addc_u32 s19, s30, s19
	s_and_b64 s[20:21], s[0:1], exec
	s_cselect_b32 s17, s19, s27
	s_cselect_b32 s51, s18, s26
	s_ashr_i32 s15, s14, 31
	s_lshl_b64 s[20:21], s[14:15], 20
	s_add_u32 s20, s31, s20
	s_addc_u32 s21, s33, s21
	s_and_b64 s[28:29], s[0:1], exec
	s_cselect_b32 s15, s21, s25
	s_cselect_b32 s52, s20, s24
	s_add_u32 s53, s24, 0x100
	s_addc_u32 s54, s25, 0
	s_add_u32 s24, s26, 0x80080
	v_mov_b32_e32 v0, 0
	s_addc_u32 s25, s27, 0
	s_mov_b32 s55, -2
	v_mov_b32_e32 v1, v0
	v_mov_b32_e32 v2, v0
	v_mov_b32_e32 v3, v0
	v_mov_b32_e32 v4, v0
	v_mov_b32_e32 v5, v0
	v_mov_b32_e32 v6, v0
	v_mov_b32_e32 v7, v0
	v_mov_b32_e32 v16, v0
	v_mov_b32_e32 v17, v0
	v_mov_b32_e32 v18, v0
	v_mov_b32_e32 v19, v0
	v_mov_b32_e32 v20, v0
	v_mov_b32_e32 v21, v0
	v_mov_b32_e32 v22, v0
	v_mov_b32_e32 v23, v0
	v_mov_b32_e32 v32, v0
	v_mov_b32_e32 v33, v0
	v_mov_b32_e32 v34, v0
	v_mov_b32_e32 v35, v0
	v_mov_b32_e32 v36, v0
	v_mov_b32_e32 v37, v0
	v_mov_b32_e32 v38, v0
	v_mov_b32_e32 v39, v0
	v_mov_b32_e32 v48, v0
	v_mov_b32_e32 v49, v0
	v_mov_b32_e32 v50, v0
	v_mov_b32_e32 v51, v0
	v_mov_b32_e32 v52, v0
	v_mov_b32_e32 v53, v0
	v_mov_b32_e32 v54, v0
	v_mov_b32_e32 v55, v0
	v_mov_b32_e32 v8, v0
	v_mov_b32_e32 v9, v0
	v_mov_b32_e32 v10, v0
	v_mov_b32_e32 v11, v0
	v_mov_b32_e32 v12, v0
	v_mov_b32_e32 v13, v0
	v_mov_b32_e32 v14, v0
	v_mov_b32_e32 v15, v0
	v_mov_b32_e32 v24, v0
	v_mov_b32_e32 v25, v0
	v_mov_b32_e32 v26, v0
	v_mov_b32_e32 v27, v0
	v_mov_b32_e32 v28, v0
	v_mov_b32_e32 v29, v0
	v_mov_b32_e32 v30, v0
	v_mov_b32_e32 v31, v0
	v_mov_b32_e32 v40, v0
	v_mov_b32_e32 v41, v0
	v_mov_b32_e32 v42, v0
	v_mov_b32_e32 v43, v0
	v_mov_b32_e32 v44, v0
	v_mov_b32_e32 v45, v0
	v_mov_b32_e32 v46, v0
	v_mov_b32_e32 v47, v0
	v_mov_b32_e32 v56, v0
	v_mov_b32_e32 v57, v0
	v_mov_b32_e32 v58, v0
	v_mov_b32_e32 v59, v0
	v_mov_b32_e32 v60, v0
	v_mov_b32_e32 v61, v0
	v_mov_b32_e32 v62, v0
	v_mov_b32_e32 v63, v0
	v_mov_b32_e32 v64, v0
	v_mov_b32_e32 v65, v0
	v_mov_b32_e32 v66, v0
	v_mov_b32_e32 v67, v0
	v_mov_b32_e32 v68, v0
	v_mov_b32_e32 v69, v0
	v_mov_b32_e32 v70, v0
	v_mov_b32_e32 v71, v0
	v_mov_b32_e32 v80, v0
	v_mov_b32_e32 v81, v0
	v_mov_b32_e32 v82, v0
	v_mov_b32_e32 v83, v0
	v_mov_b32_e32 v84, v0
	v_mov_b32_e32 v85, v0
	v_mov_b32_e32 v86, v0
	v_mov_b32_e32 v87, v0
	v_mov_b32_e32 v96, v0
	v_mov_b32_e32 v97, v0
	v_mov_b32_e32 v98, v0
	v_mov_b32_e32 v99, v0
	v_mov_b32_e32 v100, v0
	v_mov_b32_e32 v101, v0
	v_mov_b32_e32 v102, v0
	v_mov_b32_e32 v103, v0
	v_mov_b32_e32 v112, v0
	v_mov_b32_e32 v113, v0
	v_mov_b32_e32 v114, v0
	v_mov_b32_e32 v115, v0
	v_mov_b32_e32 v116, v0
	v_mov_b32_e32 v117, v0
	v_mov_b32_e32 v118, v0
	v_mov_b32_e32 v119, v0
	v_mov_b32_e32 v72, v0
	v_mov_b32_e32 v73, v0
	v_mov_b32_e32 v74, v0
	v_mov_b32_e32 v75, v0
	v_mov_b32_e32 v76, v0
	v_mov_b32_e32 v77, v0
	v_mov_b32_e32 v78, v0
	v_mov_b32_e32 v79, v0
	v_mov_b32_e32 v88, v0
	v_mov_b32_e32 v89, v0
	v_mov_b32_e32 v90, v0
	v_mov_b32_e32 v91, v0
	v_mov_b32_e32 v92, v0
	v_mov_b32_e32 v93, v0
	v_mov_b32_e32 v94, v0
	v_mov_b32_e32 v95, v0
	v_mov_b32_e32 v104, v0
	v_mov_b32_e32 v105, v0
	v_mov_b32_e32 v106, v0
	v_mov_b32_e32 v107, v0
	v_mov_b32_e32 v108, v0
	v_mov_b32_e32 v109, v0
	v_mov_b32_e32 v110, v0
	v_mov_b32_e32 v111, v0
	v_mov_b32_e32 v120, v0
	v_mov_b32_e32 v121, v0
	v_mov_b32_e32 v122, v0
	v_mov_b32_e32 v123, v0
	v_mov_b32_e32 v124, v0
	v_mov_b32_e32 v125, v0
	v_mov_b32_e32 v126, v0
	v_mov_b32_e32 v127, v0
	.p2alignl 6, 3212836864

;     __host__ __device__ bool next(int i, Unit& u) const { const long L = (long)i * G + c; if (L >= nun) return false; u.pz = (int)L / nM; u.pm = (int)L % nM; u.pn = 0; return true; }
;   __device__ __forceinline__ bool next(int i,AttnUnit&u)const{ const int v=vcu+(i>>2)*G; if(v>=256)return false; const int s=v&15,k=i&3; u.bh=v>>4; u.qb=(k&1)?(32*(k>>1)+31-s):(32*(k>>1)+s); return true; }
; template <class Epi, class Sched, bool ALIGN_EPI = false, bool SP2 = false>
; __device__ __forceinline__ void gemm_phase(PG8_LAS unsigned char* lds, const Gemm g, const Sched& S, const Epi& E, const int wid) {
;     ...
;         const bool has_next = S.next(ui + 1, nxt);
;         const char* nA = has_next ? PG8_APTR(nxt) : cA; const char* nB = has_next ? PG8_BPTR(nxt) : cB;
;         for (int t = 0; t < nt; t += 2) {
;             const bool last = (t == nt - 2);
;             const char* a1 = cA + (size_t)(t + 1) * kstep;
;             const char* a2 = last ? nA : cA + (size_t)(t + 2) * kstep; const char* b2 = last ? nB : cB + (size_t)(t + 2) * kstep;
;     ...
; #pragma unroll
;         for (int a = 0; a < 2; ++a)
; #pragma unroll
;             for (int b = 0; b < 2; ++b)
; #pragma unroll
;                 for (int m = 0; m < 4; ++m)
; #pragma unroll
;                     for (int n = 0; n < 2; ++n) acc[a][b][m][n] = (f32x4){0.f, 0.f, 0.f, 0.f};
;         cur = nxt; cA = nA; cB = nB; ++ui;
.LBB0_496:
	s_add_u32 s59, s34, 0x100
	v_mov_b32_e32 v0, 0
	s_addc_u32 s60, s35, 0
	s_mov_b32 s61, -2
	s_waitcnt lgkmcnt(0)
	v_mov_b32_e32 v1, v0
	v_mov_b32_e32 v2, v0
	v_mov_b32_e32 v3, v0
	v_mov_b32_e32 v4, v0
	v_mov_b32_e32 v5, v0
	v_mov_b32_e32 v6, v0
	v_mov_b32_e32 v7, v0
	v_mov_b32_e32 v16, v0
	v_mov_b32_e32 v17, v0
	v_mov_b32_e32 v18, v0
	v_mov_b32_e32 v19, v0
	v_mov_b32_e32 v20, v0
	v_mov_b32_e32 v21, v0
	v_mov_b32_e32 v22, v0
	v_mov_b32_e32 v23, v0
	s_waitcnt vmcnt(0)
	v_mov_b32_e32 v32, v0
	v_mov_b32_e32 v33, v0
	v_mov_b32_e32 v34, v0
	v_mov_b32_e32 v35, v0
	v_mov_b32_e32 v36, v0
	v_mov_b32_e32 v37, v0
	v_mov_b32_e32 v38, v0
	v_mov_b32_e32 v39, v0
	v_mov_b32_e32 v48, v0
	v_mov_b32_e32 v49, v0
	v_mov_b32_e32 v50, v0
	v_mov_b32_e32 v51, v0
	v_mov_b32_e32 v52, v0
	v_mov_b32_e32 v53, v0
	v_mov_b32_e32 v54, v0
	v_mov_b32_e32 v55, v0
	v_mov_b32_e32 v8, v0
	v_mov_b32_e32 v9, v0
	v_mov_b32_e32 v10, v0
	v_mov_b32_e32 v11, v0
	v_mov_b32_e32 v12, v0
	v_mov_b32_e32 v13, v0
	v_mov_b32_e32 v14, v0
	v_mov_b32_e32 v15, v0
	v_mov_b32_e32 v24, v0
	v_mov_b32_e32 v25, v0
	v_mov_b32_e32 v26, v0
	v_mov_b32_e32 v27, v0
	v_mov_b32_e32 v28, v0
	v_mov_b32_e32 v29, v0
	v_mov_b32_e32 v30, v0
	v_mov_b32_e32 v31, v0
	v_mov_b32_e32 v40, v0
	v_mov_b32_e32 v41, v0
	v_mov_b32_e32 v42, v0
	v_mov_b32_e32 v43, v0
	v_mov_b32_e32 v44, v0
	v_mov_b32_e32 v45, v0
	v_mov_b32_e32 v46, v0
	v_mov_b32_e32 v47, v0
	v_mov_b32_e32 v56, v0
	v_mov_b32_e32 v57, v0
	v_mov_b32_e32 v58, v0
	v_mov_b32_e32 v59, v0
	v_mov_b32_e32 v60, v0
	v_mov_b32_e32 v61, v0
	v_mov_b32_e32 v62, v0
	v_mov_b32_e32 v63, v0
	v_mov_b32_e32 v68, v0
	v_mov_b32_e32 v69, v0
	v_mov_b32_e32 v70, v0
	v_mov_b32_e32 v71, v0
	v_mov_b32_e32 v76, v0
	v_mov_b32_e32 v77, v0
	v_mov_b32_e32 v78, v0
	v_mov_b32_e32 v79, v0
	v_mov_b32_e32 v112, v0
	v_mov_b32_e32 v113, v0
	v_mov_b32_e32 v114, v0
	v_mov_b32_e32 v115, v0
	v_mov_b32_e32 v116, v0
	v_mov_b32_e32 v117, v0
	v_mov_b32_e32 v118, v0
	v_mov_b32_e32 v119, v0
	v_mov_b32_e32 v128, v0
	v_mov_b32_e32 v129, v0
	v_mov_b32_e32 v130, v0
	v_mov_b32_e32 v131, v0
	v_mov_b32_e32 v132, v0
	v_mov_b32_e32 v133, v0
	v_mov_b32_e32 v134, v0
	v_mov_b32_e32 v135, v0
	v_mov_b32_e32 v144, v0
	v_mov_b32_e32 v145, v0
	v_mov_b32_e32 v146, v0
	v_mov_b32_e32 v147, v0
	v_mov_b32_e32 v148, v0
	v_mov_b32_e32 v149, v0
	v_mov_b32_e32 v150, v0
	v_mov_b32_e32 v151, v0
	v_mov_b32_e32 v96, v0
	v_mov_b32_e32 v97, v0
	v_mov_b32_e32 v98, v0
	v_mov_b32_e32 v99, v0
	v_mov_b32_e32 v108, v0
	v_mov_b32_e32 v109, v0
	v_mov_b32_e32 v110, v0
	v_mov_b32_e32 v111, v0
	v_mov_b32_e32 v120, v0
	v_mov_b32_e32 v121, v0
	v_mov_b32_e32 v122, v0
	v_mov_b32_e32 v123, v0
	v_mov_b32_e32 v124, v0
	v_mov_b32_e32 v125, v0
	v_mov_b32_e32 v126, v0
	v_mov_b32_e32 v127, v0
	v_mov_b32_e32 v136, v0
	v_mov_b32_e32 v137, v0
	v_mov_b32_e32 v138, v0
	v_mov_b32_e32 v139, v0
	v_mov_b32_e32 v140, v0
	v_mov_b32_e32 v141, v0
	v_mov_b32_e32 v142, v0
	v_mov_b32_e32 v143, v0
	v_mov_b32_e32 v152, v0
	v_mov_b32_e32 v153, v0
	v_mov_b32_e32 v154, v0
	v_mov_b32_e32 v155, v0
	v_mov_b32_e32 v156, v0
	v_mov_b32_e32 v157, v0
	v_mov_b32_e32 v158, v0
	v_mov_b32_e32 v159, v0
	.p2alignl 6, 3212836864

;     __host__ __device__ bool next(int i, Unit& u) const { const long L = (long)i * G + c; if (L >= nun) return false; u.pz = (int)L / nM; u.pm = (int)L % nM; u.pn = 0; return true; }
;   __device__ __forceinline__ bool next(int i,AttnUnit&u)const{ const int v=vcu+(i>>2)*G; if(v>=256)return false; const int s=v&15,k=i&3; u.bh=v>>4; u.qb=(k&1)?(32*(k>>1)+31-s):(32*(k>>1)+s); return true; }
; template <class Epi, class Sched, bool ALIGN_EPI = false, bool SP2 = false>
; __device__ __forceinline__ void gemm_phase(PG8_LAS unsigned char* lds, const Gemm g, const Sched& S, const Epi& E, const int wid) {
;     ...
;         const bool has_next = S.next(ui + 1, nxt);
;         const char* nA = has_next ? PG8_APTR(nxt) : cA; const char* nB = has_next ? PG8_BPTR(nxt) : cB;
;         for (int t = 0; t < nt; t += 2) {
;             const bool last = (t == nt - 2);
;             const char* a1 = cA + (size_t)(t + 1) * kstep;
;             const char* a2 = last ? nA : cA + (size_t)(t + 2) * kstep; const char* b2 = last ? nB : cB + (size_t)(t + 2) * kstep;
;     ...
; #pragma unroll
;         for (int a = 0; a < 2; ++a)
; #pragma unroll
;             for (int b = 0; b < 2; ++b)
; #pragma unroll
;                 for (int m = 0; m < 4; ++m)
; #pragma unroll
;                     for (int n = 0; n < 2; ++n) acc[a][b][m][n] = (f32x4){0.f, 0.f, 0.f, 0.f};
;         cur = nxt; cA = nA; cB = nB; ++ui;
.LBB0_587:
	s_ashr_i32 s47, s46, 31
	s_lshl_b64 s[48:49], s[46:47], 20
	s_add_u32 s48, s3, s48
	s_addc_u32 s49, s33, s49
	s_and_b64 s[50:51], s[0:1], exec
	s_cselect_b32 s5, s49, s9
	s_cselect_b32 s47, s48, s8
	s_ashr_i32 s45, s44, 31
	s_lshl_b64 s[50:51], s[44:45], 20
	s_add_u32 s50, s56, s50
	s_addc_u32 s51, s57, s51
	s_and_b64 s[52:53], s[0:1], exec
	s_cselect_b32 s45, s51, s7
	s_cselect_b32 s54, s50, s6
	s_add_u32 s55, s6, 0x100
	s_addc_u32 s86, s7, 0
	s_add_u32 s6, s8, 0x80080
	v_mov_b32_e32 v0, 0
	s_addc_u32 s7, s9, 0
	s_mov_b32 s87, -2
	v_mov_b32_e32 v1, v0
	v_mov_b32_e32 v2, v0
	v_mov_b32_e32 v3, v0
	v_mov_b32_e32 v4, v0
	v_mov_b32_e32 v5, v0
	v_mov_b32_e32 v6, v0
	v_mov_b32_e32 v7, v0
	v_mov_b32_e32 v16, v0
	v_mov_b32_e32 v17, v0
	v_mov_b32_e32 v18, v0
	v_mov_b32_e32 v19, v0
	v_mov_b32_e32 v20, v0
	v_mov_b32_e32 v21, v0
	v_mov_b32_e32 v22, v0
	v_mov_b32_e32 v23, v0
	s_waitcnt vmcnt(0)
	v_mov_b32_e32 v32, v0
	v_mov_b32_e32 v33, v0
	v_mov_b32_e32 v34, v0
	v_mov_b32_e32 v35, v0
	v_mov_b32_e32 v36, v0
	v_mov_b32_e32 v37, v0
	v_mov_b32_e32 v38, v0
	v_mov_b32_e32 v39, v0
	s_waitcnt lgkmcnt(0)
	v_mov_b32_e32 v48, v0
	v_mov_b32_e32 v49, v0
	v_mov_b32_e32 v50, v0
	v_mov_b32_e32 v51, v0
	v_mov_b32_e32 v52, v0
	v_mov_b32_e32 v53, v0
	v_mov_b32_e32 v54, v0
	v_mov_b32_e32 v55, v0
	v_mov_b32_e32 v8, v0
	v_mov_b32_e32 v9, v0
	v_mov_b32_e32 v10, v0
	v_mov_b32_e32 v11, v0
	v_mov_b32_e32 v12, v0
	v_mov_b32_e32 v13, v0
	v_mov_b32_e32 v14, v0
	v_mov_b32_e32 v15, v0
	v_mov_b32_e32 v24, v0
	v_mov_b32_e32 v25, v0
	v_mov_b32_e32 v26, v0
	v_mov_b32_e32 v27, v0
	v_mov_b32_e32 v28, v0
	v_mov_b32_e32 v29, v0
	v_mov_b32_e32 v30, v0
	v_mov_b32_e32 v31, v0
	v_mov_b32_e32 v40, v0
	v_mov_b32_e32 v41, v0
	v_mov_b32_e32 v42, v0
	v_mov_b32_e32 v43, v0
	v_mov_b32_e32 v44, v0
	v_mov_b32_e32 v45, v0
	v_mov_b32_e32 v46, v0
	v_mov_b32_e32 v47, v0
	v_mov_b32_e32 v56, v0
	v_mov_b32_e32 v57, v0
	v_mov_b32_e32 v58, v0
	v_mov_b32_e32 v59, v0
	v_mov_b32_e32 v60, v0
	v_mov_b32_e32 v61, v0
	v_mov_b32_e32 v62, v0
	v_mov_b32_e32 v63, v0
	v_mov_b32_e32 v64, v0
	v_mov_b32_e32 v65, v0
	v_mov_b32_e32 v66, v0
	v_mov_b32_e32 v67, v0
	v_mov_b32_e32 v68, v0
	v_mov_b32_e32 v69, v0
	v_mov_b32_e32 v70, v0
	v_mov_b32_e32 v71, v0
	v_mov_b32_e32 v80, v0
	v_mov_b32_e32 v81, v0
	v_mov_b32_e32 v82, v0
	v_mov_b32_e32 v83, v0
	v_mov_b32_e32 v84, v0
	v_mov_b32_e32 v85, v0
	v_mov_b32_e32 v86, v0
	v_mov_b32_e32 v87, v0
	v_mov_b32_e32 v96, v0
	v_mov_b32_e32 v97, v0
	v_mov_b32_e32 v98, v0
	v_mov_b32_e32 v99, v0
	v_mov_b32_e32 v100, v0
	v_mov_b32_e32 v101, v0
	v_mov_b32_e32 v102, v0
	v_mov_b32_e32 v103, v0
	v_mov_b32_e32 v112, v0
	v_mov_b32_e32 v113, v0
	v_mov_b32_e32 v114, v0
	v_mov_b32_e32 v115, v0
	v_mov_b32_e32 v116, v0
	v_mov_b32_e32 v117, v0
	v_mov_b32_e32 v118, v0
	v_mov_b32_e32 v119, v0
	v_mov_b32_e32 v72, v0
	v_mov_b32_e32 v73, v0
	v_mov_b32_e32 v74, v0
	v_mov_b32_e32 v75, v0
	v_mov_b32_e32 v76, v0
	v_mov_b32_e32 v77, v0
	v_mov_b32_e32 v78, v0
	v_mov_b32_e32 v79, v0
	v_mov_b32_e32 v88, v0
	v_mov_b32_e32 v89, v0
	v_mov_b32_e32 v90, v0
	v_mov_b32_e32 v91, v0
	v_mov_b32_e32 v92, v0
	v_mov_b32_e32 v93, v0
	v_mov_b32_e32 v94, v0
	v_mov_b32_e32 v95, v0
	v_mov_b32_e32 v104, v0
	v_mov_b32_e32 v105, v0
	v_mov_b32_e32 v106, v0
	v_mov_b32_e32 v107, v0
	v_mov_b32_e32 v108, v0
	v_mov_b32_e32 v109, v0
	v_mov_b32_e32 v110, v0
	v_mov_b32_e32 v111, v0
	v_mov_b32_e32 v120, v0
	v_mov_b32_e32 v121, v0
	v_mov_b32_e32 v122, v0
	v_mov_b32_e32 v123, v0
	v_mov_b32_e32 v124, v0
	v_mov_b32_e32 v125, v0
	v_mov_b32_e32 v126, v0
	v_mov_b32_e32 v127, v0
	.p2alignl 6, 3212836864

; #define WAIT_BAR(N) asm volatile("s_waitcnt vmcnt(" #N ") lgkmcnt(0)\n\ts_barrier":::"memory")
;   #define DMA_K(t,slot) glds16(ksrc+(long)(t)*KVBLK*DM,(unsigned)__builtin_amdgcn_readfirstlane(kdst+(slot)))
;   #define DMA_V(t,slot) do{ glds16(vsrc+(long)(t)*KVBLK*DM,(unsigned)__builtin_amdgcn_readfirstlane(vdst+2*(slot))); glds16(vsrc+64+(long)(t)*KVBLK*DM,(unsigned)__builtin_amdgcn_readfirstlane(vdst+2*(slot)+8192)); }while(0)
;   #define ROT() do{sl_prev=sl_cur;sl_cur=sl_next;sl_next=(sl_next==(NSLOT-1)*SLOTB)?0:sl_next+SLOTB;}while(0)
; template<int THRL,bool FIXED> __device__ __forceinline__ void attn_unit(int qb,const bf16*Q,const bf16*__restrict__ Kh,const bf16*__restrict__ Vh,bf16*O,const int*__restrict__ cid,char*shm,const int wid){
;     ...
;   _Pragma("unroll") for(int r=0;r<16;++r)pA1[r]=__builtin_amdgcn_exp2f(pA1[r]);
;   WAIT_BAR(0);
;   DMA_K(3,0);DMA_V(1,SLOTB);
;   ROT();
;   kload8(kf,kp0+sl_cur);
;   WAIT_BAR(3);
;   s16x4 vlo[8],vhi[8]; u32x4 pw0,pw1,pw2,pw3;
;     ...
;   int t=1;
;     ...
;   for(;t+5<NT;t+=2){
.LBB0_1060:
	s_waitcnt vmcnt(0) lgkmcnt(0)
	s_barrier
	s_nop 10
	v_exp_f32_e32 v82, v2
	v_exp_f32_e32 v83, v3
	v_lshl_add_u64 v[2:3], v[34:35], 0, s[66:67]
	s_mov_b32 s0, m0
	s_mov_b32 m0, s96
	s_nop 0
	global_load_lds_dwordx4 v[2:3], off
	s_mov_b32 m0, s0
	s_cmp_lg_u32 0, -1
	s_cselect_b32 s0, 0, 0
	s_add_i32 s0, s0, s3
	v_lshl_add_u64 v[2:3], v[36:37], 0, s[14:15]
	s_add_i32 s1, s0, 0xa000
	s_mov_b32 s4, m0
	s_mov_b32 m0, s1
	s_nop 0
	global_load_lds_dwordx4 v[2:3], off
	s_mov_b32 m0, s4
	v_lshl_add_u64 v[2:3], v[36:37], 0, s[74:75]
	s_add_i32 s0, s0, 0xc000
	s_mov_b32 s1, m0
	s_mov_b32 m0, s0
	s_nop 0
	global_load_lds_dwordx4 v[2:3], off
	s_mov_b32 m0, s1
	ds_read_b128 v[206:209], v238 offset:8192
	ds_read_b128 v[202:205], v238 offset:8704
	ds_read_b128 v[198:201], v238 offset:10240
	ds_read_b128 v[194:197], v238 offset:10752
	ds_read_b128 v[190:193], v238 offset:12288
	ds_read_b128 v[186:189], v238 offset:12800
	ds_read_b128 v[182:185], v238 offset:14336
	ds_read_b128 v[178:181], v238 offset:14848
	v_lshlrev_b32_e32 v0, 1, v222
	v_and_b32_e32 v239, 32, v0
	v_lshlrev_b32_e32 v0, 4, v222
	v_and_b32_e32 v0, 0xc0, v0
	v_exp_f32_e32 v98, v18
	v_exp_f32_e32 v99, v19
	v_exp_f32_e32 v100, v20
	v_exp_f32_e32 v101, v21
	v_exp_f32_e32 v102, v22
	v_exp_f32_e32 v103, v23
	v_exp_f32_e32 v104, v24
	v_exp_f32_e32 v105, v25
	v_exp_f32_e32 v106, v26
	v_exp_f32_e32 v107, v27
	v_exp_f32_e32 v108, v28
	v_exp_f32_e32 v109, v29
	v_exp_f32_e32 v110, v30
	v_exp_f32_e32 v111, v31
	v_exp_f32_e32 v112, v32
	v_exp_f32_e32 v113, v33
	v_exp_f32_e32 v84, v4
	v_exp_f32_e32 v85, v5
	v_exp_f32_e32 v86, v6
	v_exp_f32_e32 v87, v7
	v_exp_f32_e32 v88, v8
	v_exp_f32_e32 v89, v9
	v_exp_f32_e32 v90, v10
	v_exp_f32_e32 v91, v11
	v_exp_f32_e32 v92, v12
	v_exp_f32_e32 v93, v13
	v_exp_f32_e32 v94, v14
	v_exp_f32_e32 v95, v15
	v_exp_f32_e32 v96, v16
	v_exp_f32_e32 v97, v17
	v_lshl_or_b32 v235, v234, 8, v0
	v_add_u32_e32 v0, 0, v239
	s_waitcnt vmcnt(3) lgkmcnt(0)
	s_barrier
	v_add3_u32 v240, v0, v237, v235
	v_and_b32_e32 v0, 3, v222
	s_mov_b32 s10, 1
	s_mov_b32 s34, 0
	s_mov_b32 s4, 0
	s_cmp_lt_i32 s13, 7
	v_lshlrev_b32_e32 v0, 4, v0
	s_cbranch_scc1 .LBB0_1068
	v_readlane_b32 s30, v254, 10
	s_add_i32 s0, s13, -5
	v_readlane_b32 s31, v254, 11
	v_readlane_b32 s1, v254, 7
	v_mov_b32_e32 v66, 0
	v_lshl_add_u64 v[2:3], s[30:31], 0, v[212:213]
	s_add_u32 s30, s52, s1
	v_lshl_add_u64 v[2:3], v[2:3], 0, v[0:1]
	s_addc_u32 s31, s53, 0
	v_lshl_add_u64 v[214:215], s[54:55], 1, v[2:3]
	v_lshl_add_u64 v[216:217], s[30:31], 0, v[210:211]
	s_movk_i32 s18, 0x4000
	s_movk_i32 s12, 0x2000
	v_mov_b32_e32 v34, 0
	v_mov_b32_e32 v35, v66
	v_mov_b32_e32 v36, v66
	v_mov_b32_e32 v37, v66
	v_mov_b32_e32 v38, v66
	v_mov_b32_e32 v39, v66
	v_mov_b32_e32 v40, v66
	v_mov_b32_e32 v41, v66
	v_mov_b32_e32 v42, v66
	v_mov_b32_e32 v43, v66
	v_mov_b32_e32 v44, v66
	v_mov_b32_e32 v45, v66
	v_mov_b32_e32 v46, v66
	v_mov_b32_e32 v47, v66
	v_mov_b32_e32 v48, v66
	v_mov_b32_e32 v49, v66
	v_mov_b32_e32 v50, 0
	v_mov_b32_e32 v51, v66
	v_mov_b32_e32 v52, v66
	v_mov_b32_e32 v53, v66
	v_mov_b32_e32 v54, v66
	v_mov_b32_e32 v55, v66
	v_mov_b32_e32 v56, v66
	v_mov_b32_e32 v57, v66
	v_mov_b32_e32 v58, v66
	v_mov_b32_e32 v59, v66
	v_mov_b32_e32 v60, v66
	v_mov_b32_e32 v61, v66
	v_mov_b32_e32 v62, v66
	v_mov_b32_e32 v63, v66
	v_mov_b32_e32 v64, v66
	v_mov_b32_e32 v65, v66
	v_mov_b32_e32 v2, 0
	v_mov_b32_e32 v3, v66
	v_mov_b32_e32 v4, v66
	v_mov_b32_e32 v5, v66
	v_mov_b32_e32 v6, v66
	v_mov_b32_e32 v7, v66
	v_mov_b32_e32 v8, v66
	v_mov_b32_e32 v9, v66
	v_mov_b32_e32 v10, v66
	v_mov_b32_e32 v11, v66
	v_mov_b32_e32 v12, v66
	v_mov_b32_e32 v13, v66
	v_mov_b32_e32 v14, v66
	v_mov_b32_e32 v15, v66
	v_mov_b32_e32 v16, v66
	v_mov_b32_e32 v17, v66
	v_mov_b32_e32 v18, 0
	v_mov_b32_e32 v19, v66
	v_mov_b32_e32 v20, v66
	v_mov_b32_e32 v21, v66
	v_mov_b32_e32 v22, v66
	v_mov_b32_e32 v23, v66
	v_mov_b32_e32 v24, v66
	v_mov_b32_e32 v25, v66
	v_mov_b32_e32 v26, v66
	v_mov_b32_e32 v27, v66
	v_mov_b32_e32 v28, v66
	v_mov_b32_e32 v29, v66
	v_mov_b32_e32 v30, v66
	v_mov_b32_e32 v31, v66
	v_mov_b32_e32 v32, v66
	v_mov_b32_e32 v33, v66
	.p2alignl 6, 3212836864

;     __host__ __device__ bool next(int i, Unit& u) const { const long L = (long)i * G + c; if (L >= nun) return false; u.pz = (int)L / nM; u.pm = (int)L % nM; u.pn = 0; return true; }
;   __device__ __forceinline__ bool next(int i,AttnUnit&u)const{ const int v=vcu+(i>>2)*G; if(v>=256)return false; const int s=v&15,k=i&3; u.bh=v>>4; u.qb=(k&1)?(32*(k>>1)+31-s):(32*(k>>1)+s); return true; }
; template <class Epi, class Sched, bool ALIGN_EPI = false, bool SP2 = false>
; __device__ __forceinline__ void gemm_phase(PG8_LAS unsigned char* lds, const Gemm g, const Sched& S, const Epi& E, const int wid) {
;     ...
;         const bool has_next = S.next(ui + 1, nxt);
;         const char* nA = has_next ? PG8_APTR(nxt) : cA; const char* nB = has_next ? PG8_BPTR(nxt) : cB;
;         for (int t = 0; t < nt; t += 2) {
;             const bool last = (t == nt - 2);
;             const char* a1 = cA + (size_t)(t + 1) * kstep;
;             const char* a2 = last ? nA : cA + (size_t)(t + 2) * kstep; const char* b2 = last ? nB : cB + (size_t)(t + 2) * kstep;
;     ...
; #pragma unroll
;         for (int a = 0; a < 2; ++a)
; #pragma unroll
;             for (int b = 0; b < 2; ++b)
; #pragma unroll
;                 for (int m = 0; m < 4; ++m)
; #pragma unroll
;                     for (int n = 0; n < 2; ++n) acc[a][b][m][n] = (f32x4){0.f, 0.f, 0.f, 0.f};
;         cur = nxt; cA = nA; cB = nB; ++ui;
.LBB0_1176:
	s_ashr_i32 s29, s28, 31
	s_lshl_b64 s[30:31], s[28:29], 19
	s_add_u32 s30, s8, s30
	s_addc_u32 s31, s9, s31
	s_and_b64 s[34:35], s[0:1], exec
	s_cselect_b32 s29, s31, s41
	s_cselect_b32 s60, s30, s40
	s_ashr_i32 s27, s26, 31
	s_lshl_b64 s[34:35], s[26:27], 19
	s_add_u32 s34, s33, s34
	s_addc_u32 s35, s44, s35
	s_and_b64 s[42:43], s[0:1], exec
	s_cselect_b32 s27, s35, s39
	s_cselect_b32 s61, s34, s38
	s_add_u32 s62, s38, 0x100
	s_addc_u32 s63, s39, 0
	s_add_u32 s38, s40, 0x40080
	v_mov_b32_e32 v0, 0
	s_addc_u32 s39, s41, 0
	s_mov_b32 s64, -2
	v_mov_b32_e32 v1, v0
	v_mov_b32_e32 v2, v0
	v_mov_b32_e32 v3, v0
	v_mov_b32_e32 v4, v0
	v_mov_b32_e32 v5, v0
	v_mov_b32_e32 v6, v0
	v_mov_b32_e32 v7, v0
	v_mov_b32_e32 v8, v0
	v_mov_b32_e32 v9, v0
	v_mov_b32_e32 v10, v0
	v_mov_b32_e32 v11, v0
	v_mov_b32_e32 v12, v0
	v_mov_b32_e32 v13, v0
	v_mov_b32_e32 v14, v0
	v_mov_b32_e32 v15, v0
	v_mov_b32_e32 v16, v0
	v_mov_b32_e32 v17, v0
	v_mov_b32_e32 v18, v0
	v_mov_b32_e32 v19, v0
	v_mov_b32_e32 v20, v0
	v_mov_b32_e32 v21, v0
	v_mov_b32_e32 v22, v0
	v_mov_b32_e32 v23, v0
	v_mov_b32_e32 v24, v0
	v_mov_b32_e32 v25, v0
	v_mov_b32_e32 v26, v0
	v_mov_b32_e32 v27, v0
	v_mov_b32_e32 v28, v0
	v_mov_b32_e32 v29, v0
	v_mov_b32_e32 v30, v0
	v_mov_b32_e32 v31, v0
	s_waitcnt vmcnt(0)
	v_mov_b32_e32 v64, v0
	v_mov_b32_e32 v65, v0
	v_mov_b32_e32 v66, v0
	v_mov_b32_e32 v67, v0
	v_mov_b32_e32 v68, v0
	v_mov_b32_e32 v69, v0
	v_mov_b32_e32 v70, v0
	v_mov_b32_e32 v71, v0
	v_mov_b32_e32 v72, v0
	v_mov_b32_e32 v73, v0
	v_mov_b32_e32 v74, v0
	v_mov_b32_e32 v75, v0
	v_mov_b32_e32 v76, v0
	v_mov_b32_e32 v77, v0
	v_mov_b32_e32 v78, v0
	v_mov_b32_e32 v79, v0
	v_mov_b32_e32 v80, v0
	v_mov_b32_e32 v81, v0
	v_mov_b32_e32 v82, v0
	v_mov_b32_e32 v83, v0
	v_mov_b32_e32 v84, v0
	v_mov_b32_e32 v85, v0
	v_mov_b32_e32 v86, v0
	v_mov_b32_e32 v87, v0
	v_mov_b32_e32 v88, v0
	v_mov_b32_e32 v89, v0
	v_mov_b32_e32 v90, v0
	v_mov_b32_e32 v91, v0
	v_mov_b32_e32 v92, v0
	v_mov_b32_e32 v93, v0
	v_mov_b32_e32 v94, v0
	v_mov_b32_e32 v95, v0
	v_mov_b32_e32 v32, v0
	v_mov_b32_e32 v33, v0
	v_mov_b32_e32 v34, v0
	v_mov_b32_e32 v35, v0
	v_mov_b32_e32 v36, v0
	v_mov_b32_e32 v37, v0
	v_mov_b32_e32 v38, v0
	v_mov_b32_e32 v39, v0
	v_mov_b32_e32 v40, v0
	v_mov_b32_e32 v41, v0
	v_mov_b32_e32 v42, v0
	v_mov_b32_e32 v43, v0
	v_mov_b32_e32 v44, v0
	v_mov_b32_e32 v45, v0
	v_mov_b32_e32 v46, v0
	v_mov_b32_e32 v47, v0
	v_mov_b32_e32 v48, v0
	v_mov_b32_e32 v49, v0
	v_mov_b32_e32 v50, v0
	v_mov_b32_e32 v51, v0
	v_mov_b32_e32 v52, v0
	v_mov_b32_e32 v53, v0
	v_mov_b32_e32 v54, v0
	v_mov_b32_e32 v55, v0
	v_mov_b32_e32 v56, v0
	v_mov_b32_e32 v57, v0
	v_mov_b32_e32 v58, v0
	v_mov_b32_e32 v59, v0
	v_mov_b32_e32 v60, v0
	v_mov_b32_e32 v61, v0
	v_mov_b32_e32 v62, v0
	v_mov_b32_e32 v63, v0
	v_mov_b32_e32 v96, v0
	v_mov_b32_e32 v97, v0
	v_mov_b32_e32 v98, v0
	v_mov_b32_e32 v99, v0
	v_mov_b32_e32 v100, v0
	v_mov_b32_e32 v101, v0
	v_mov_b32_e32 v102, v0
	v_mov_b32_e32 v103, v0
	v_mov_b32_e32 v104, v0
	v_mov_b32_e32 v105, v0
	v_mov_b32_e32 v106, v0
	v_mov_b32_e32 v107, v0
	v_mov_b32_e32 v108, v0
	v_mov_b32_e32 v109, v0
	v_mov_b32_e32 v110, v0
	v_mov_b32_e32 v111, v0
	v_mov_b32_e32 v112, v0
	v_mov_b32_e32 v113, v0
	v_mov_b32_e32 v114, v0
	v_mov_b32_e32 v115, v0
	v_mov_b32_e32 v116, v0
	v_mov_b32_e32 v117, v0
	v_mov_b32_e32 v118, v0
	v_mov_b32_e32 v119, v0
	v_mov_b32_e32 v120, v0
	v_mov_b32_e32 v121, v0
	v_mov_b32_e32 v122, v0
	v_mov_b32_e32 v123, v0
	v_mov_b32_e32 v124, v0
	v_mov_b32_e32 v125, v0
	v_mov_b32_e32 v126, v0
	v_mov_b32_e32 v127, v0
	.p2alignl 6, 3212836864

;     __host__ __device__ bool next(int i, Unit& u) const { const long L = (long)i * G + c; if (L >= nun) return false; u.pz = (int)L / nM; u.pm = (int)L % nM; u.pn = 0; return true; }
;   __device__ __forceinline__ bool next(int i,AttnUnit&u)const{ const int v=vcu+(i>>2)*G; if(v>=256)return false; const int s=v&15,k=i&3; u.bh=v>>4; u.qb=(k&1)?(32*(k>>1)+31-s):(32*(k>>1)+s); return true; }
; template <class Epi, class Sched, bool ALIGN_EPI = false, bool SP2 = false>
; __device__ __forceinline__ void gemm_phase(PG8_LAS unsigned char* lds, const Gemm g, const Sched& S, const Epi& E, const int wid) {
;     ...
;         const bool has_next = S.next(ui + 1, nxt);
;         const char* nA = has_next ? PG8_APTR(nxt) : cA; const char* nB = has_next ? PG8_BPTR(nxt) : cB;
;         for (int t = 0; t < nt; t += 2) {
;             const bool last = (t == nt - 2);
;             const char* a1 = cA + (size_t)(t + 1) * kstep;
;             const char* a2 = last ? nA : cA + (size_t)(t + 2) * kstep; const char* b2 = last ? nB : cB + (size_t)(t + 2) * kstep;
;     ...
; #pragma unroll
;         for (int a = 0; a < 2; ++a)
; #pragma unroll
;             for (int b = 0; b < 2; ++b)
; #pragma unroll
;                 for (int m = 0; m < 4; ++m)
; #pragma unroll
;                     for (int n = 0; n < 2; ++n) acc[a][b][m][n] = (f32x4){0.f, 0.f, 0.f, 0.f};
;         cur = nxt; cA = nA; cB = nB; ++ui;
.LBB0_1303:
	s_ashr_i32 s27, s26, 31
	s_lshl_b64 s[28:29], s[26:27], 20
	s_add_u32 s28, s3, s28
	s_addc_u32 s29, s33, s29
	s_and_b64 s[30:31], s[0:1], exec
	s_cselect_b32 s5, s29, s39
	s_cselect_b32 s27, s28, s38
	s_ashr_i32 s25, s24, 31
	s_lshl_b64 s[30:31], s[24:25], 20
	s_add_u32 s30, s42, s30
	s_addc_u32 s31, s43, s31
	s_and_b64 s[40:41], s[0:1], exec
	s_cselect_b32 s25, s31, s37
	s_cselect_b32 s58, s30, s36
	s_add_u32 s59, s36, 0x100
	s_addc_u32 s60, s37, 0
	s_add_u32 s36, s38, 0x80080
	v_mov_b32_e32 v0, 0
	s_addc_u32 s37, s39, 0
	s_mov_b32 s61, -2
	s_waitcnt lgkmcnt(0)
	v_mov_b32_e32 v1, v0
	v_mov_b32_e32 v2, v0
	v_mov_b32_e32 v3, v0
	v_mov_b32_e32 v4, v0
	v_mov_b32_e32 v5, v0
	v_mov_b32_e32 v6, v0
	v_mov_b32_e32 v7, v0
	v_mov_b32_e32 v16, v0
	v_mov_b32_e32 v17, v0
	v_mov_b32_e32 v18, v0
	v_mov_b32_e32 v19, v0
	v_mov_b32_e32 v20, v0
	v_mov_b32_e32 v21, v0
	v_mov_b32_e32 v22, v0
	v_mov_b32_e32 v23, v0
	s_waitcnt vmcnt(0)
	v_mov_b32_e32 v32, v0
	v_mov_b32_e32 v33, v0
	v_mov_b32_e32 v34, v0
	v_mov_b32_e32 v35, v0
	v_mov_b32_e32 v36, v0
	v_mov_b32_e32 v37, v0
	v_mov_b32_e32 v38, v0
	v_mov_b32_e32 v39, v0
	v_mov_b32_e32 v48, v0
	v_mov_b32_e32 v49, v0
	v_mov_b32_e32 v50, v0
	v_mov_b32_e32 v51, v0
	v_mov_b32_e32 v52, v0
	v_mov_b32_e32 v53, v0
	v_mov_b32_e32 v54, v0
	v_mov_b32_e32 v55, v0
	v_mov_b32_e32 v8, v0
	v_mov_b32_e32 v9, v0
	v_mov_b32_e32 v10, v0
	v_mov_b32_e32 v11, v0
	v_mov_b32_e32 v12, v0
	v_mov_b32_e32 v13, v0
	v_mov_b32_e32 v14, v0
	v_mov_b32_e32 v15, v0
	v_mov_b32_e32 v24, v0
	v_mov_b32_e32 v25, v0
	v_mov_b32_e32 v26, v0
	v_mov_b32_e32 v27, v0
	v_mov_b32_e32 v28, v0
	v_mov_b32_e32 v29, v0
	v_mov_b32_e32 v30, v0
	v_mov_b32_e32 v31, v0
	v_mov_b32_e32 v40, v0
	v_mov_b32_e32 v41, v0
	v_mov_b32_e32 v42, v0
	v_mov_b32_e32 v43, v0
	v_mov_b32_e32 v44, v0
	v_mov_b32_e32 v45, v0
	v_mov_b32_e32 v46, v0
	v_mov_b32_e32 v47, v0
	v_mov_b32_e32 v56, v0
	v_mov_b32_e32 v57, v0
	v_mov_b32_e32 v58, v0
	v_mov_b32_e32 v59, v0
	v_mov_b32_e32 v60, v0
	v_mov_b32_e32 v61, v0
	v_mov_b32_e32 v62, v0
	v_mov_b32_e32 v63, v0
	v_mov_b32_e32 v68, v0
	v_mov_b32_e32 v69, v0
	v_mov_b32_e32 v70, v0
	v_mov_b32_e32 v71, v0
	v_mov_b32_e32 v76, v0
	v_mov_b32_e32 v77, v0
	v_mov_b32_e32 v78, v0
	v_mov_b32_e32 v79, v0
	v_mov_b32_e32 v112, v0
	v_mov_b32_e32 v113, v0
	v_mov_b32_e32 v114, v0
	v_mov_b32_e32 v115, v0
	v_mov_b32_e32 v116, v0
	v_mov_b32_e32 v117, v0
	v_mov_b32_e32 v118, v0
	v_mov_b32_e32 v119, v0
	v_mov_b32_e32 v128, v0
	v_mov_b32_e32 v129, v0
	v_mov_b32_e32 v130, v0
	v_mov_b32_e32 v131, v0
	v_mov_b32_e32 v132, v0
	v_mov_b32_e32 v133, v0
	v_mov_b32_e32 v134, v0
	v_mov_b32_e32 v135, v0
	v_mov_b32_e32 v144, v0
	v_mov_b32_e32 v145, v0
	v_mov_b32_e32 v146, v0
	v_mov_b32_e32 v147, v0
	v_mov_b32_e32 v148, v0
	v_mov_b32_e32 v149, v0
	v_mov_b32_e32 v150, v0
	v_mov_b32_e32 v151, v0
	v_mov_b32_e32 v96, v0
	v_mov_b32_e32 v97, v0
	v_mov_b32_e32 v98, v0
	v_mov_b32_e32 v99, v0
	v_mov_b32_e32 v108, v0
	v_mov_b32_e32 v109, v0
	v_mov_b32_e32 v110, v0
	v_mov_b32_e32 v111, v0
	v_mov_b32_e32 v120, v0
	v_mov_b32_e32 v121, v0
	v_mov_b32_e32 v122, v0
	v_mov_b32_e32 v123, v0
	v_mov_b32_e32 v124, v0
	v_mov_b32_e32 v125, v0
	v_mov_b32_e32 v126, v0
	v_mov_b32_e32 v127, v0
	v_mov_b32_e32 v136, v0
	v_mov_b32_e32 v137, v0
	v_mov_b32_e32 v138, v0
	v_mov_b32_e32 v139, v0
	v_mov_b32_e32 v140, v0
	v_mov_b32_e32 v141, v0
	v_mov_b32_e32 v142, v0
	v_mov_b32_e32 v143, v0
	v_mov_b32_e32 v152, v0
	v_mov_b32_e32 v153, v0
	v_mov_b32_e32 v154, v0
	v_mov_b32_e32 v155, v0
	v_mov_b32_e32 v156, v0
	v_mov_b32_e32 v157, v0
	v_mov_b32_e32 v158, v0
	v_mov_b32_e32 v159, v0
	.p2alignl 6, 3212836864

;     __host__ __device__ bool next(int i, Unit& u) const { const long L = (long)i * G + c; if (L >= nun) return false; u.pz = (int)L / nM; u.pm = (int)L % nM; u.pn = 0; return true; }
;   __device__ __forceinline__ bool next(int i,AttnUnit&u)const{ const int v=vcu+(i>>2)*G; if(v>=256)return false; const int s=v&15,k=i&3; u.bh=v>>4; u.qb=(k&1)?(32*(k>>1)+31-s):(32*(k>>1)+s); return true; }
; template <class Epi, class Sched, bool ALIGN_EPI = false, bool SP2 = false>
; __device__ __forceinline__ void gemm_phase(PG8_LAS unsigned char* lds, const Gemm g, const Sched& S, const Epi& E, const int wid) {
;     ...
;         const bool has_next = S.next(ui + 1, nxt);
;         const char* nA = has_next ? PG8_APTR(nxt) : cA; const char* nB = has_next ? PG8_BPTR(nxt) : cB;
;         for (int t = 0; t < nt; t += 2) {
;             const bool last = (t == nt - 2);
;             const char* a1 = cA + (size_t)(t + 1) * kstep;
;             const char* a2 = last ? nA : cA + (size_t)(t + 2) * kstep; const char* b2 = last ? nB : cB + (size_t)(t + 2) * kstep;
;     ...
; #pragma unroll
;         for (int a = 0; a < 2; ++a)
; #pragma unroll
;             for (int b = 0; b < 2; ++b)
; #pragma unroll
;                 for (int m = 0; m < 4; ++m)
; #pragma unroll
;                     for (int n = 0; n < 2; ++n) acc[a][b][m][n] = (f32x4){0.f, 0.f, 0.f, 0.f};
;         cur = nxt; cA = nA; cB = nB; ++ui;
.LBB0_1384:
	s_ashr_i32 s25, s24, 31
	s_lshl_b64 s[26:27], s[24:25], 20
	s_add_u32 s26, s3, s26
	s_addc_u32 s27, s33, s27
	s_and_b64 s[28:29], s[0:1], exec
	s_cselect_b32 s5, s27, s9
	s_cselect_b32 s25, s26, s8
	s_ashr_i32 s23, s22, 31
	s_lshl_b64 s[28:29], s[22:23], 20
	s_add_u32 s28, s34, s28
	s_addc_u32 s29, s35, s29
	s_and_b64 s[30:31], s[0:1], exec
	s_cselect_b32 s23, s29, s7
	s_cselect_b32 s57, s28, s6
	s_add_u32 s58, s6, 0x100
	s_addc_u32 s59, s7, 0
	s_add_u32 s6, s8, 0x80080
	v_mov_b32_e32 v0, 0
	s_addc_u32 s7, s9, 0
	s_mov_b32 s60, -2
	v_mov_b32_e32 v1, v0
	v_mov_b32_e32 v2, v0
	v_mov_b32_e32 v3, v0
	v_mov_b32_e32 v4, v0
	v_mov_b32_e32 v5, v0
	v_mov_b32_e32 v6, v0
	v_mov_b32_e32 v7, v0
	v_mov_b32_e32 v16, v0
	v_mov_b32_e32 v17, v0
	v_mov_b32_e32 v18, v0
	v_mov_b32_e32 v19, v0
	v_mov_b32_e32 v20, v0
	v_mov_b32_e32 v21, v0
	v_mov_b32_e32 v22, v0
	v_mov_b32_e32 v23, v0
	s_waitcnt vmcnt(0)
	v_mov_b32_e32 v32, v0
	v_mov_b32_e32 v33, v0
	v_mov_b32_e32 v34, v0
	v_mov_b32_e32 v35, v0
	v_mov_b32_e32 v36, v0
	v_mov_b32_e32 v37, v0
	v_mov_b32_e32 v38, v0
	v_mov_b32_e32 v39, v0
	v_mov_b32_e32 v48, v0
	v_mov_b32_e32 v49, v0
	v_mov_b32_e32 v50, v0
	v_mov_b32_e32 v51, v0
	v_mov_b32_e32 v52, v0
	v_mov_b32_e32 v53, v0
	v_mov_b32_e32 v54, v0
	v_mov_b32_e32 v55, v0
	v_mov_b32_e32 v8, v0
	v_mov_b32_e32 v9, v0
	v_mov_b32_e32 v10, v0
	v_mov_b32_e32 v11, v0
	v_mov_b32_e32 v12, v0
	v_mov_b32_e32 v13, v0
	v_mov_b32_e32 v14, v0
	v_mov_b32_e32 v15, v0
	v_mov_b32_e32 v24, v0
	v_mov_b32_e32 v25, v0
	v_mov_b32_e32 v26, v0
	v_mov_b32_e32 v27, v0
	v_mov_b32_e32 v28, v0
	v_mov_b32_e32 v29, v0
	v_mov_b32_e32 v30, v0
	v_mov_b32_e32 v31, v0
	v_mov_b32_e32 v40, v0
	v_mov_b32_e32 v41, v0
	v_mov_b32_e32 v42, v0
	v_mov_b32_e32 v43, v0
	v_mov_b32_e32 v44, v0
	v_mov_b32_e32 v45, v0
	v_mov_b32_e32 v46, v0
	v_mov_b32_e32 v47, v0
	v_mov_b32_e32 v56, v0
	v_mov_b32_e32 v57, v0
	v_mov_b32_e32 v58, v0
	v_mov_b32_e32 v59, v0
	v_mov_b32_e32 v60, v0
	v_mov_b32_e32 v61, v0
	v_mov_b32_e32 v62, v0
	v_mov_b32_e32 v63, v0
	v_mov_b32_e32 v64, v0
	v_mov_b32_e32 v65, v0
	v_mov_b32_e32 v66, v0
	v_mov_b32_e32 v67, v0
	v_mov_b32_e32 v68, v0
	v_mov_b32_e32 v69, v0
	v_mov_b32_e32 v70, v0
	v_mov_b32_e32 v71, v0
	v_mov_b32_e32 v80, v0
	v_mov_b32_e32 v81, v0
	v_mov_b32_e32 v82, v0
	v_mov_b32_e32 v83, v0
	v_mov_b32_e32 v84, v0
	v_mov_b32_e32 v85, v0
	v_mov_b32_e32 v86, v0
	v_mov_b32_e32 v87, v0
	v_mov_b32_e32 v96, v0
	v_mov_b32_e32 v97, v0
	v_mov_b32_e32 v98, v0
	v_mov_b32_e32 v99, v0
	v_mov_b32_e32 v100, v0
	v_mov_b32_e32 v101, v0
	v_mov_b32_e32 v102, v0
	v_mov_b32_e32 v103, v0
	v_mov_b32_e32 v112, v0
	v_mov_b32_e32 v113, v0
	v_mov_b32_e32 v114, v0
	v_mov_b32_e32 v115, v0
	v_mov_b32_e32 v116, v0
	v_mov_b32_e32 v117, v0
	v_mov_b32_e32 v118, v0
	v_mov_b32_e32 v119, v0
	v_mov_b32_e32 v72, v0
	v_mov_b32_e32 v73, v0
	v_mov_b32_e32 v74, v0
	v_mov_b32_e32 v75, v0
	v_mov_b32_e32 v76, v0
	v_mov_b32_e32 v77, v0
	v_mov_b32_e32 v78, v0
	v_mov_b32_e32 v79, v0
	v_mov_b32_e32 v88, v0
	v_mov_b32_e32 v89, v0
	v_mov_b32_e32 v90, v0
	v_mov_b32_e32 v91, v0
	v_mov_b32_e32 v92, v0
	v_mov_b32_e32 v93, v0
	v_mov_b32_e32 v94, v0
	v_mov_b32_e32 v95, v0
	v_mov_b32_e32 v104, v0
	v_mov_b32_e32 v105, v0
	v_mov_b32_e32 v106, v0
	v_mov_b32_e32 v107, v0
	v_mov_b32_e32 v108, v0
	v_mov_b32_e32 v109, v0
	v_mov_b32_e32 v110, v0
	v_mov_b32_e32 v111, v0
	v_mov_b32_e32 v120, v0
	v_mov_b32_e32 v121, v0
	v_mov_b32_e32 v122, v0
	v_mov_b32_e32 v123, v0
	v_mov_b32_e32 v124, v0
	v_mov_b32_e32 v125, v0
	v_mov_b32_e32 v126, v0
	v_mov_b32_e32 v127, v0
	.p2alignl 6, 3212836864

;     __host__ __device__ bool next(int i, Unit& u) const { const long L = (long)i * G + c; if (L >= nun) return false; u.pz = (int)L / nM; u.pm = (int)L % nM; u.pn = 0; return true; }
;   __device__ __forceinline__ bool next(int i,AttnUnit&u)const{ const int v=vcu+(i>>2)*G; if(v>=256)return false; const int s=v&15,k=i&3; u.bh=v>>4; u.qb=(k&1)?(32*(k>>1)+31-s):(32*(k>>1)+s); return true; }
; template <class Epi, class Sched, bool ALIGN_EPI = false, bool SP2 = false>
; __device__ __forceinline__ void gemm_phase(PG8_LAS unsigned char* lds, const Gemm g, const Sched& S, const Epi& E, const int wid) {
;     ...
;         const bool has_next = S.next(ui + 1, nxt);
;         const char* nA = has_next ? PG8_APTR(nxt) : cA; const char* nB = has_next ? PG8_BPTR(nxt) : cB;
;         for (int t = 0; t < nt; t += 2) {
;             const bool last = (t == nt - 2);
;             const char* a1 = cA + (size_t)(t + 1) * kstep;
;             const char* a2 = last ? nA : cA + (size_t)(t + 2) * kstep; const char* b2 = last ? nB : cB + (size_t)(t + 2) * kstep;
;     ...
; #pragma unroll
;         for (int a = 0; a < 2; ++a)
; #pragma unroll
;             for (int b = 0; b < 2; ++b)
; #pragma unroll
;                 for (int m = 0; m < 4; ++m)
; #pragma unroll
;                     for (int n = 0; n < 2; ++n) acc[a][b][m][n] = (f32x4){0.f, 0.f, 0.f, 0.f};
;         cur = nxt; cA = nA; cB = nB; ++ui;
.LBB0_1461:
	s_add_u32 s56, s28, 0x100
	v_mov_b32_e32 v0, 0
	s_addc_u32 s57, s29, 0
	s_mov_b32 s58, -2
	v_mov_b32_e32 v1, v0
	v_mov_b32_e32 v2, v0
	v_mov_b32_e32 v3, v0
	v_mov_b32_e32 v4, v0
	v_mov_b32_e32 v5, v0
	v_mov_b32_e32 v6, v0
	v_mov_b32_e32 v7, v0
	v_mov_b32_e32 v8, v0
	v_mov_b32_e32 v9, v0
	v_mov_b32_e32 v10, v0
	v_mov_b32_e32 v11, v0
	v_mov_b32_e32 v12, v0
	v_mov_b32_e32 v13, v0
	v_mov_b32_e32 v14, v0
	v_mov_b32_e32 v15, v0
	s_waitcnt vmcnt(0)
	v_mov_b32_e32 v32, v0
	v_mov_b32_e32 v33, v0
	v_mov_b32_e32 v34, v0
	v_mov_b32_e32 v35, v0
	v_mov_b32_e32 v36, v0
	v_mov_b32_e32 v37, v0
	v_mov_b32_e32 v38, v0
	v_mov_b32_e32 v39, v0
	v_mov_b32_e32 v40, v0
	v_mov_b32_e32 v41, v0
	v_mov_b32_e32 v42, v0
	v_mov_b32_e32 v43, v0
	v_mov_b32_e32 v44, v0
	v_mov_b32_e32 v45, v0
	v_mov_b32_e32 v46, v0
	v_mov_b32_e32 v47, v0
	v_mov_b32_e32 v16, v0
	v_mov_b32_e32 v17, v0
	v_mov_b32_e32 v18, v0
	v_mov_b32_e32 v19, v0
	v_mov_b32_e32 v20, v0
	v_mov_b32_e32 v21, v0
	v_mov_b32_e32 v22, v0
	v_mov_b32_e32 v23, v0
	v_mov_b32_e32 v24, v0
	v_mov_b32_e32 v25, v0
	v_mov_b32_e32 v26, v0
	v_mov_b32_e32 v27, v0
	v_mov_b32_e32 v28, v0
	v_mov_b32_e32 v29, v0
	v_mov_b32_e32 v30, v0
	v_mov_b32_e32 v31, v0
	v_mov_b32_e32 v48, v0
	v_mov_b32_e32 v49, v0
	v_mov_b32_e32 v50, v0
	v_mov_b32_e32 v51, v0
	v_mov_b32_e32 v52, v0
	v_mov_b32_e32 v53, v0
	v_mov_b32_e32 v54, v0
	v_mov_b32_e32 v55, v0
	v_mov_b32_e32 v56, v0
	v_mov_b32_e32 v57, v0
	v_mov_b32_e32 v58, v0
	v_mov_b32_e32 v59, v0
	v_mov_b32_e32 v60, v0
	v_mov_b32_e32 v61, v0
	v_mov_b32_e32 v62, v0
	v_mov_b32_e32 v63, v0
	v_mov_b32_e32 v64, v0
	v_mov_b32_e32 v65, v0
	v_mov_b32_e32 v66, v0
	v_mov_b32_e32 v67, v0
	v_mov_b32_e32 v68, v0
	v_mov_b32_e32 v69, v0
	v_mov_b32_e32 v70, v0
	v_mov_b32_e32 v71, v0
	v_mov_b32_e32 v72, v0
	v_mov_b32_e32 v73, v0
	v_mov_b32_e32 v74, v0
	v_mov_b32_e32 v75, v0
	v_mov_b32_e32 v76, v0
	v_mov_b32_e32 v77, v0
	v_mov_b32_e32 v78, v0
	v_mov_b32_e32 v79, v0
	v_mov_b32_e32 v96, v0
	v_mov_b32_e32 v97, v0
	v_mov_b32_e32 v98, v0
	v_mov_b32_e32 v99, v0
	v_mov_b32_e32 v100, v0
	v_mov_b32_e32 v101, v0
	v_mov_b32_e32 v102, v0
	v_mov_b32_e32 v103, v0
	v_mov_b32_e32 v104, v0
	v_mov_b32_e32 v105, v0
	v_mov_b32_e32 v106, v0
	v_mov_b32_e32 v107, v0
	v_mov_b32_e32 v108, v0
	v_mov_b32_e32 v109, v0
	v_mov_b32_e32 v110, v0
	v_mov_b32_e32 v111, v0
	v_mov_b32_e32 v80, v0
	v_mov_b32_e32 v81, v0
	v_mov_b32_e32 v82, v0
	v_mov_b32_e32 v83, v0
	v_mov_b32_e32 v84, v0
	v_mov_b32_e32 v85, v0
	v_mov_b32_e32 v86, v0
	v_mov_b32_e32 v87, v0
	v_mov_b32_e32 v88, v0
	v_mov_b32_e32 v89, v0
	v_mov_b32_e32 v90, v0
	v_mov_b32_e32 v91, v0
	v_mov_b32_e32 v92, v0
	v_mov_b32_e32 v93, v0
	v_mov_b32_e32 v94, v0
	v_mov_b32_e32 v95, v0
	v_mov_b32_e32 v112, v0
	v_mov_b32_e32 v113, v0
	v_mov_b32_e32 v114, v0
	v_mov_b32_e32 v115, v0
	v_mov_b32_e32 v116, v0
	v_mov_b32_e32 v117, v0
	v_mov_b32_e32 v118, v0
	v_mov_b32_e32 v119, v0
	v_mov_b32_e32 v120, v0
	v_mov_b32_e32 v121, v0
	v_mov_b32_e32 v122, v0
	v_mov_b32_e32 v123, v0
	v_mov_b32_e32 v124, v0
	v_mov_b32_e32 v125, v0
	v_mov_b32_e32 v126, v0
	v_mov_b32_e32 v127, v0
	.p2alignl 6, 3212836864
